# pass A gates: wait-state nops left over from the removed log1p expansion deleted
# speedup vs baseline: 1.0078x; 1.0022x over previous
.LBB0_675:
	s_and_b64 s[10:11], vcc, exec
	s_movk_i32 s4, 0x68
	s_cselect_b32 s4, s4, 0x78
	s_add_u32 s10, s8, s4
	s_addc_u32 s11, s9, 0
	s_waitcnt lgkmcnt(0)
	s_barrier
	v_and_b32_e32 v3, 63, v2
	v_lshlrev_b32_e32 v0, 2, v3
	s_waitcnt lgkmcnt(0)
	s_add_u32 s4, s10, s22
	s_addc_u32 s5, s11, s23
	s_lshl_b32 s7, s6, 2
	s_add_u32 s10, s4, s7
	s_addc_u32 s11, s5, 0
	v_lshl_add_u64 v[8:9], s[10:11], 0, v[0:1]
	v_add_co_u32_e64 v34, s[40:41], s37, v8
	s_and_b64 s[14:15], vcc, exec
	s_nop 0
	v_addc_co_u32_e64 v35, s[40:41], 0, v9, s[40:41]
	s_movk_i32 s4, 0x70
	v_add_co_u32_e64 v36, s[40:41], s85, v8
	s_cselect_b32 s4, s4, 0x80
	s_nop 0
	v_addc_co_u32_e64 v37, s[40:41], 0, v9, s[40:41]
	s_add_u32 s14, s8, s4
	v_add_co_u32_e64 v26, s[40:41], s68, v8
	s_addc_u32 s15, s9, 0
	v_addc_co_u32_e64 v27, s[40:41], 0, v9, s[40:41]
	v_readlane_b32 s4, v254, 41
	s_or_b32 s4, s6, s4
	v_or_b32_e32 v26, s4, v3
	v_mov_b32_e32 v27, v1
	s_waitcnt lgkmcnt(0)
	v_lshl_add_u64 v[26:27], v[26:27], 2, s[14:15]
	s_nop 0
	s_waitcnt vmcnt(0)
	v_mov_b32_e32 v29, v132
	v_mov_b32_e32 v30, v133
	v_mov_b32_e32 v31, v134
	v_mov_b32_e32 v32, v135
	v_mov_b32_e32 v28, v136
	v_mov_b32_e32 v27, v137
	v_mov_b32_e32 v12, v138
	v_mov_b32_e32 v13, v139
	v_mov_b32_e32 v6, v140
	v_mov_b32_e32 v7, v141
	v_mov_b32_e32 v4, v142
	v_mov_b32_e32 v5, v143
	v_mov_b32_e32 v8, v144
	v_mov_b32_e32 v9, v145
	v_mov_b32_e32 v10, v146
	v_mov_b32_e32 v11, v147
	v_mov_b32_e32 v26, v148
	v_ashrrev_i32_e32 v3, 6, v2
	v_lshl_add_u32 v25, v3, 9, 0
	ds_read_b128 v[34:37], v25 offset:27664
	ds_read_b128 v[38:41], v25 offset:27680
	ds_read_b128 v[42:45], v25 offset:27696
	ds_read_b128 v[46:49], v25 offset:27648
	s_mov_b32 s4, 0x3d800000
	v_lshl_add_u32 v2, v2, 2, 0
	v_add_u32_e32 v0, 0, v0
	v_readlane_b32 s5, v254, 42
	s_waitcnt vmcnt(15) lgkmcnt(2)
	v_pk_mul_f32 v[38:39], v[6:7], v[38:39]
	s_waitcnt vmcnt(13)
	v_pk_mul_f32 v[40:41], v[4:5], v[40:41]
	s_waitcnt vmcnt(11)
	v_pk_mul_f32 v[36:37], v[12:13], v[36:37]
	s_waitcnt vmcnt(9) lgkmcnt(1)
	v_pk_mul_f32 v[42:43], v[8:9], v[42:43]
	s_waitcnt vmcnt(5) lgkmcnt(0)
	v_fma_f32 v33, v29, v46, v26
	s_waitcnt vmcnt(4)
	v_fmac_f32_e32 v33, v30, v47
	s_waitcnt vmcnt(3)
	v_fmac_f32_e32 v33, v31, v48
	s_waitcnt vmcnt(2)
	v_fmac_f32_e32 v33, v32, v49
	s_waitcnt vmcnt(1)
	v_fmac_f32_e32 v33, v28, v34
	s_waitcnt vmcnt(0)
	v_fmac_f32_e32 v33, v27, v35
	v_add_f32_e32 v33, v33, v36
	v_add_f32_e32 v33, v33, v37
	v_add_f32_e32 v33, v33, v38
	v_add_f32_e32 v33, v33, v39
	v_add_f32_e32 v33, v33, v40
	v_add_f32_e32 v33, v33, v41
	v_add_f32_e32 v33, v33, v42
	v_pk_mul_f32 v[44:45], v[10:11], v[44:45]
	v_add_f32_e32 v33, v33, v43
	v_add_f32_e32 v33, v33, v44
	v_add_f32_e32 v33, v33, v45
	v_mul_f32_e64 v34, |v33|, s90
	v_exp_f32_e32 v38, v34
	v_min_f32_e32 v33, 0, v33
	ds_read_b128 v[34:37], v25 offset:27712
	v_add_f32_e32 v150, 1.0, v38
	s_nop 0
	v_add_f32_e32 v151, -1.0, v150
	v_log_f32_e32 v152, v150
	v_rcp_f32_e32 v153, v151
	s_nop 0
	v_mul_f32_e32 v152, 0x3f317218, v152
	v_mul_f32_e32 v153, v38, v153
	v_cmp_eq_f32_e32 vcc, 0, v151
	v_mul_f32_e32 v152, v152, v153
	s_nop 0
	v_cndmask_b32_e32 v42, v152, v38, vcc
	ds_read_b128 v[38:41], v25 offset:27728
	s_waitcnt lgkmcnt(1)
	v_fma_f32 v43, v29, v34, v26
	v_fmac_f32_e32 v43, v30, v35
	v_fmac_f32_e32 v43, v31, v36
	v_fmac_f32_e32 v43, v32, v37
	ds_read_b128 v[34:37], v25 offset:27744
	s_waitcnt lgkmcnt(1)
	v_fmac_f32_e32 v43, v28, v38
	v_fmac_f32_e32 v43, v27, v39
	v_pk_mul_f32 v[38:39], v[12:13], v[40:41]
	v_sub_f32_e32 v33, v33, v42
	v_add_f32_e32 v38, v43, v38
	v_add_f32_e32 v43, v38, v39
	ds_read_b128 v[38:41], v25 offset:27760
	s_waitcnt lgkmcnt(1)
	v_pk_mul_f32 v[34:35], v[6:7], v[34:35]
	v_fma_f32 v33, v33, s4, 0
	v_add_f32_e32 v34, v43, v34
	v_add_f32_e32 v43, v34, v35
	v_pk_mul_f32 v[34:35], v[4:5], v[36:37]
	s_nop 0
	v_add_f32_e32 v34, v43, v34
	v_add_f32_e32 v36, v34, v35
	s_waitcnt lgkmcnt(0)
	v_pk_mul_f32 v[34:35], v[8:9], v[38:39]
	s_nop 0
	v_add_f32_e32 v34, v36, v34
	v_add_f32_e32 v36, v34, v35
	v_pk_mul_f32 v[34:35], v[10:11], v[40:41]
	s_nop 0
	v_add_f32_e32 v34, v36, v34
	v_add_f32_e32 v34, v34, v35
	v_mul_f32_e64 v35, |v34|, s90
	v_exp_f32_e32 v38, v35
	v_min_f32_e32 v42, 0, v34
	ds_read_b128 v[34:37], v25 offset:27776
	v_add_f32_e32 v150, 1.0, v38
	s_nop 0
	v_add_f32_e32 v151, -1.0, v150
	v_log_f32_e32 v152, v150
	v_rcp_f32_e32 v153, v151
	s_nop 0
	v_mul_f32_e32 v152, 0x3f317218, v152
	v_mul_f32_e32 v153, v38, v153
	v_cmp_eq_f32_e32 vcc, 0, v151
	v_mul_f32_e32 v152, v152, v153
	s_nop 0
	v_cndmask_b32_e32 v43, v152, v38, vcc
	ds_read_b128 v[38:41], v25 offset:27792
	s_waitcnt lgkmcnt(1)
	v_fma_f32 v44, v29, v34, v26
	v_fmac_f32_e32 v44, v30, v35
	v_fmac_f32_e32 v44, v31, v36
	v_fmac_f32_e32 v44, v32, v37
	ds_read_b128 v[34:37], v25 offset:27808
	s_waitcnt lgkmcnt(1)
	v_fmac_f32_e32 v44, v28, v38
	v_fmac_f32_e32 v44, v27, v39
	v_pk_mul_f32 v[38:39], v[12:13], v[40:41]
	s_nop 0
	v_add_f32_e32 v38, v44, v38
	v_add_f32_e32 v44, v38, v39
	ds_read_b128 v[38:41], v25 offset:27824
	s_waitcnt lgkmcnt(1)
	v_pk_mul_f32 v[34:35], v[6:7], v[34:35]
	s_nop 0
	v_add_f32_e32 v34, v44, v34
	v_add_f32_e32 v44, v34, v35
	v_pk_mul_f32 v[34:35], v[4:5], v[36:37]
	s_nop 0
	v_add_f32_e32 v34, v44, v34
	v_add_f32_e32 v36, v34, v35
	s_waitcnt lgkmcnt(0)
	v_pk_mul_f32 v[34:35], v[8:9], v[38:39]
	s_nop 0
	v_add_f32_e32 v34, v36, v34
	v_add_f32_e32 v36, v34, v35
	v_pk_mul_f32 v[34:35], v[10:11], v[40:41]
	s_nop 0
	v_add_f32_e32 v34, v36, v34
	v_add_f32_e32 v35, v34, v35
	v_mul_f32_e64 v34, |v35|, s90
	v_exp_f32_e32 v40, v34
	v_sub_f32_e32 v34, v42, v43
	v_min_f32_e32 v35, 0, v35
	v_fmamk_f32 v34, v34, 0x3d800000, v33
	ds_read_b128 v[36:39], v25 offset:27840
	v_add_f32_e32 v150, 1.0, v40
	s_nop 0
	v_add_f32_e32 v151, -1.0, v150
	v_log_f32_e32 v152, v150
	v_rcp_f32_e32 v153, v151
	s_nop 0
	v_mul_f32_e32 v152, 0x3f317218, v152
	v_mul_f32_e32 v153, v40, v153
	v_cmp_eq_f32_e32 vcc, 0, v151
	v_mul_f32_e32 v152, v152, v153
	s_nop 0
	v_cndmask_b32_e32 v44, v152, v40, vcc
	ds_read_b128 v[40:43], v25 offset:27856
	s_waitcnt lgkmcnt(1)
	v_fma_f32 v45, v29, v36, v26
	v_fmac_f32_e32 v45, v30, v37
	v_fmac_f32_e32 v45, v31, v38
	v_fmac_f32_e32 v45, v32, v39
	ds_read_b128 v[36:39], v25 offset:27872
	s_waitcnt lgkmcnt(1)
	v_fmac_f32_e32 v45, v28, v40
	v_fmac_f32_e32 v45, v27, v41
	v_pk_mul_f32 v[40:41], v[12:13], v[42:43]
	v_sub_f32_e32 v35, v35, v44
	v_add_f32_e32 v40, v45, v40
	v_add_f32_e32 v45, v40, v41
	ds_read_b128 v[40:43], v25 offset:27888
	s_waitcnt lgkmcnt(1)
	v_pk_mul_f32 v[36:37], v[6:7], v[36:37]
	v_fmamk_f32 v35, v35, 0x3d800000, v34
	v_add_f32_e32 v36, v45, v36
	v_add_f32_e32 v45, v36, v37
	v_pk_mul_f32 v[36:37], v[4:5], v[38:39]
	s_nop 0
	v_add_f32_e32 v36, v45, v36
	v_add_f32_e32 v38, v36, v37
	s_waitcnt lgkmcnt(0)
	v_pk_mul_f32 v[36:37], v[8:9], v[40:41]
	s_nop 0
	v_add_f32_e32 v36, v38, v36
	v_add_f32_e32 v38, v36, v37
	v_pk_mul_f32 v[36:37], v[10:11], v[42:43]
	s_nop 0
	v_add_f32_e32 v36, v38, v36
	v_add_f32_e32 v36, v36, v37
	v_mul_f32_e64 v37, |v36|, s90
	v_exp_f32_e32 v40, v37
	v_min_f32_e32 v44, 0, v36
	ds_read_b128 v[36:39], v25 offset:27904
	v_add_f32_e32 v150, 1.0, v40
	s_nop 0
	v_add_f32_e32 v151, -1.0, v150
	v_log_f32_e32 v152, v150
	v_rcp_f32_e32 v153, v151
	s_nop 0
	v_mul_f32_e32 v152, 0x3f317218, v152
	v_mul_f32_e32 v153, v40, v153
	v_cmp_eq_f32_e32 vcc, 0, v151
	v_mul_f32_e32 v152, v152, v153
	s_nop 0
	v_cndmask_b32_e32 v45, v152, v40, vcc
	ds_read_b128 v[40:43], v25 offset:27920
	s_waitcnt lgkmcnt(1)
	v_fma_f32 v46, v29, v36, v26
	v_fmac_f32_e32 v46, v30, v37
	v_fmac_f32_e32 v46, v31, v38
	v_fmac_f32_e32 v46, v32, v39
	ds_read_b128 v[36:39], v25 offset:27936
	s_waitcnt lgkmcnt(1)
	v_fmac_f32_e32 v46, v28, v40
	v_fmac_f32_e32 v46, v27, v41
	v_pk_mul_f32 v[40:41], v[12:13], v[42:43]
	s_nop 0
	v_add_f32_e32 v40, v46, v40
	v_add_f32_e32 v46, v40, v41
	ds_read_b128 v[40:43], v25 offset:27952
	s_waitcnt lgkmcnt(1)
	v_pk_mul_f32 v[36:37], v[6:7], v[36:37]
	s_nop 0
	v_add_f32_e32 v36, v46, v36
	v_add_f32_e32 v46, v36, v37
	v_pk_mul_f32 v[36:37], v[4:5], v[38:39]
	s_nop 0
	v_add_f32_e32 v36, v46, v36
	v_add_f32_e32 v38, v36, v37
	s_waitcnt lgkmcnt(0)
	v_pk_mul_f32 v[36:37], v[8:9], v[40:41]
	s_nop 0
	v_add_f32_e32 v36, v38, v36
	v_add_f32_e32 v38, v36, v37
	v_pk_mul_f32 v[36:37], v[10:11], v[42:43]
	s_nop 0
	v_add_f32_e32 v36, v38, v36
	v_add_f32_e32 v37, v36, v37
	v_mul_f32_e64 v36, |v37|, s90
	v_exp_f32_e32 v42, v36
	v_sub_f32_e32 v36, v44, v45
	v_min_f32_e32 v37, 0, v37
	v_fmamk_f32 v36, v36, 0x3d800000, v35
	ds_read_b128 v[38:41], v25 offset:27968
	v_add_f32_e32 v150, 1.0, v42
	s_nop 0
	v_add_f32_e32 v151, -1.0, v150
	v_log_f32_e32 v152, v150
	v_rcp_f32_e32 v153, v151
	s_nop 0
	v_mul_f32_e32 v152, 0x3f317218, v152
	v_mul_f32_e32 v153, v42, v153
	v_cmp_eq_f32_e32 vcc, 0, v151
	v_mul_f32_e32 v152, v152, v153
	s_nop 0
	v_cndmask_b32_e32 v46, v152, v42, vcc
	ds_read_b128 v[42:45], v25 offset:27984
	s_waitcnt lgkmcnt(1)
	v_fma_f32 v47, v29, v38, v26
	v_fmac_f32_e32 v47, v30, v39
	v_fmac_f32_e32 v47, v31, v40
	v_fmac_f32_e32 v47, v32, v41
	ds_read_b128 v[38:41], v25 offset:28000
	s_waitcnt lgkmcnt(1)
	v_fmac_f32_e32 v47, v28, v42
	v_fmac_f32_e32 v47, v27, v43
	v_pk_mul_f32 v[42:43], v[12:13], v[44:45]
	v_sub_f32_e32 v37, v37, v46
	v_add_f32_e32 v42, v47, v42
	v_add_f32_e32 v47, v42, v43
	ds_read_b128 v[42:45], v25 offset:28016
	s_waitcnt lgkmcnt(1)
	v_pk_mul_f32 v[38:39], v[6:7], v[38:39]
	v_fmamk_f32 v37, v37, 0x3d800000, v36
	v_add_f32_e32 v38, v47, v38
	v_add_f32_e32 v47, v38, v39
	v_pk_mul_f32 v[38:39], v[4:5], v[40:41]
	s_nop 0
	v_add_f32_e32 v38, v47, v38
	v_add_f32_e32 v40, v38, v39
	s_waitcnt lgkmcnt(0)
	v_pk_mul_f32 v[38:39], v[8:9], v[42:43]
	s_nop 0
	v_add_f32_e32 v38, v40, v38
	v_add_f32_e32 v40, v38, v39
	v_pk_mul_f32 v[38:39], v[10:11], v[44:45]
	s_nop 0
	v_add_f32_e32 v38, v40, v38
	v_add_f32_e32 v38, v38, v39
	v_mul_f32_e64 v39, |v38|, s90
	v_exp_f32_e32 v52, v39
	v_min_f32_e32 v53, 0, v38
	ds_read_b128 v[38:41], v25 offset:28032
	v_add_f32_e32 v150, 1.0, v52
	s_nop 0
	v_add_f32_e32 v151, -1.0, v150
	v_log_f32_e32 v152, v150
	v_rcp_f32_e32 v153, v151
	s_nop 0
	v_mul_f32_e32 v152, 0x3f317218, v152
	v_mul_f32_e32 v153, v52, v153
	v_cmp_eq_f32_e32 vcc, 0, v151
	v_mul_f32_e32 v152, v152, v153
	s_nop 0
	v_cndmask_b32_e32 v46, v152, v52, vcc
	ds_read_b128 v[42:45], v25 offset:28048
	s_waitcnt lgkmcnt(1)
	v_fma_f32 v47, v29, v38, v26
	v_fmac_f32_e32 v47, v30, v39
	v_fmac_f32_e32 v47, v31, v40
	v_fmac_f32_e32 v47, v32, v41
	ds_read_b128 v[38:41], v25 offset:28064
	s_waitcnt lgkmcnt(1)
	v_fmac_f32_e32 v47, v28, v42
	v_fmac_f32_e32 v47, v27, v43
	v_pk_mul_f32 v[42:43], v[12:13], v[44:45]
	s_nop 0
	v_add_f32_e32 v42, v47, v42
	v_add_f32_e32 v47, v42, v43
	ds_read_b128 v[42:45], v25 offset:28080
	s_waitcnt lgkmcnt(1)
	v_pk_mul_f32 v[38:39], v[6:7], v[38:39]
	s_nop 0
	v_add_f32_e32 v38, v47, v38
	v_add_f32_e32 v47, v38, v39
	v_pk_mul_f32 v[38:39], v[4:5], v[40:41]
	s_nop 0
	v_add_f32_e32 v38, v47, v38
	v_add_f32_e32 v40, v38, v39
	s_waitcnt lgkmcnt(0)
	v_pk_mul_f32 v[38:39], v[8:9], v[42:43]
	s_nop 0
	v_add_f32_e32 v38, v40, v38
	v_add_f32_e32 v40, v38, v39
	v_pk_mul_f32 v[38:39], v[10:11], v[44:45]
	s_nop 0
	v_add_f32_e32 v38, v40, v38
	v_add_f32_e32 v38, v38, v39
	v_mul_f32_e64 v39, |v38|, s90
	v_exp_f32_e32 v52, v39
	v_sub_f32_e32 v39, v53, v46
	v_min_f32_e32 v54, 0, v38
	v_fmamk_f32 v53, v39, 0x3d800000, v37
	ds_read_b128 v[38:41], v25 offset:28096
	v_add_f32_e32 v150, 1.0, v52
	s_nop 0
	v_add_f32_e32 v151, -1.0, v150
	v_log_f32_e32 v152, v150
	v_rcp_f32_e32 v153, v151
	s_nop 0
	v_mul_f32_e32 v152, 0x3f317218, v152
	v_mul_f32_e32 v153, v52, v153
	v_cmp_eq_f32_e32 vcc, 0, v151
	v_mul_f32_e32 v152, v152, v153
	s_nop 0
	v_cndmask_b32_e32 v46, v152, v52, vcc
	ds_read_b128 v[42:45], v25 offset:28112
	s_waitcnt lgkmcnt(1)
	v_fmac_f32_e32 v26, v29, v38
	v_fmac_f32_e32 v26, v30, v39
	v_fmac_f32_e32 v26, v31, v40
	v_fmac_f32_e32 v26, v32, v41
	s_waitcnt lgkmcnt(0)
	v_fmac_f32_e32 v26, v28, v42
	ds_read_b128 v[28:31], v25 offset:28128
	ds_read_b128 v[38:41], v25 offset:28144
	v_fmac_f32_e32 v26, v27, v43
	v_pk_mul_f32 v[12:13], v[12:13], v[44:45]
	s_waitcnt lgkmcnt(1)
	v_pk_mul_f32 v[6:7], v[6:7], v[28:29]
	v_add_f32_e32 v12, v26, v12
	v_add_f32_e32 v12, v12, v13
	v_add_f32_e32 v6, v12, v6
	v_add_f32_e32 v6, v6, v7
	v_pk_mul_f32 v[4:5], v[4:5], v[30:31]
	s_nop 0
	v_add_f32_e32 v4, v6, v4
	v_add_f32_e32 v6, v4, v5
	s_waitcnt lgkmcnt(0)
	v_pk_mul_f32 v[4:5], v[8:9], v[38:39]
	s_nop 0
	v_add_f32_e32 v4, v6, v4
	v_add_f32_e32 v6, v4, v5
	v_pk_mul_f32 v[4:5], v[10:11], v[40:41]
	s_nop 0
	v_add_f32_e32 v4, v6, v4
	v_add_f32_e32 v4, v4, v5
	v_mul_f32_e64 v5, |v4|, s90
	v_exp_f32_e32 v25, v5
	v_sub_f32_e32 v5, v54, v46
	v_min_f32_e32 v31, 0, v4
	v_fmamk_f32 v30, v5, 0x3d800000, v53
	v_add_f32_e32 v150, 1.0, v25
	s_nop 0
	v_add_f32_e32 v151, -1.0, v150
	v_log_f32_e32 v152, v150
	v_rcp_f32_e32 v153, v151
	s_nop 0
	v_mul_f32_e32 v152, 0x3f317218, v152
	v_mul_f32_e32 v153, v25, v153
	v_cmp_eq_f32_e32 vcc, 0, v151
	v_mul_f32_e32 v152, v152, v153
	s_nop 0
	v_cndmask_b32_e32 v4, v152, v25, vcc
	v_sub_f32_e32 v4, v31, v4
	v_fmamk_f32 v5, v4, 0x3d800000, v30
	ds_write_b32 v2, v5 offset:31744
	s_waitcnt lgkmcnt(0)
	s_barrier
	ds_read2st64_b32 v[6:7], v0 offset0:124 offset1:125
	ds_read2st64_b32 v[8:9], v0 offset0:126 offset1:127
	ds_read2st64_b32 v[10:11], v0 offset0:128 offset1:129
	ds_read2st64_b32 v[12:13], v0 offset0:130 offset1:131
	v_cmp_lt_i32_e32 vcc, 0, v3
	s_waitcnt lgkmcnt(3)
	v_add_f32_e32 v0, 0, v6
	s_waitcnt lgkmcnt(0)
	v_cndmask_b32_e32 v2, 0, v0, vcc
	v_add_f32_e32 v4, v7, v2
	v_cmp_lt_i32_e32 vcc, 1, v3
	v_add_f32_e32 v0, v0, v7
	v_add_f32_e32 v0, v0, v8
	v_cndmask_b32_e32 v2, v2, v4, vcc
	v_add_f32_e32 v4, v8, v2
	v_cmp_lt_i32_e32 vcc, 2, v3
	v_add_f32_e32 v0, v0, v9
	v_add_f32_e32 v0, v0, v10
	v_cndmask_b32_e32 v2, v2, v4, vcc
	v_add_f32_e32 v4, v9, v2
	v_cmp_lt_i32_e32 vcc, 3, v3
	v_add_f32_e32 v0, v0, v11
	v_lshlrev_b32_e32 v7, 16, v21
	v_cndmask_b32_e32 v2, v2, v4, vcc
	v_add_f32_e32 v4, v10, v2
	v_cmp_lt_i32_e32 vcc, 4, v3
	v_lshlrev_b32_e32 v9, 16, v22
	v_lshlrev_b32_e32 v8, 16, v17
	v_cndmask_b32_e32 v2, v2, v4, vcc
	v_add_f32_e32 v4, v11, v2
	v_cmp_lt_i32_e32 vcc, 5, v3
	v_lshlrev_b32_e32 v11, 16, v24
	v_lshlrev_b32_e32 v10, 16, v20
	v_cndmask_b32_e32 v2, v2, v4, vcc
	v_add_f32_e32 v4, v12, v2
	v_cmp_lt_i32_e32 vcc, 6, v3
	s_barrier
	s_nop 0
	v_cndmask_b32_e32 v2, v2, v4, vcc
	v_add_f32_e32 v4, v13, v2
	v_cmp_lt_i32_e32 vcc, 7, v3
	s_nop 1
	v_cndmask_b32_e32 v3, v2, v4, vcc
	v_add_f32_e32 v4, v0, v12
	v_mov_b32_e32 v2, v13
	v_add_f32_e32 v6, v33, v3
	v_add_f32_e32 v25, v34, v3
	v_add_f32_e32 v26, v35, v3
	v_add_f32_e32 v27, v36, v3
	v_add_f32_e32 v28, v3, v37
	v_add_f32_e32 v29, v3, v53
	v_add_f32_e32 v30, v3, v30
	v_pk_add_f32 v[2:3], v[4:5], v[2:3]
	v_mov_b32_e32 v80, v6
	v_mov_b32_e32 v81, v25
	v_mov_b32_e32 v82, v26
	v_mov_b32_e32 v83, v27
	v_mov_b32_e32 v84, v28
	v_mov_b32_e32 v85, v29
	v_mov_b32_e32 v86, v30
	v_mov_b32_e32 v87, v3
	v_lshlrev_b32_e32 v88, 5, v202
	s_lshl_b32 s98, s30, 14
	s_add_u32 s98, s98, 0x4f28000
	s_add_u32 s98, s100, s98
	s_addc_u32 s99, s101, 0
	global_store_dwordx4 v88, v[80:83], s[98:99]
	global_store_dwordx4 v88, v[84:87], s[98:99] offset:16
	v_cmp_gt_i32_e32 vcc, 64, v18
	v_sub_f32_e32 v0, v2, v6
	v_mul_f32_e32 v0, 0x3fb8aa3b, v0
	v_exp_f32_e32 v4, v0
	v_sub_f32_e32 v0, v2, v25
	v_mul_f32_e32 v0, 0x3fb8aa3b, v0
	v_exp_f32_e32 v5, v0
	v_sub_f32_e32 v0, v2, v26
	v_lshlrev_b32_e32 v6, 16, v16
	v_mul_f32_e32 v0, 0x3fb8aa3b, v0
	v_pk_mul_f32 v[4:5], v[4:5], v[6:7]
	v_exp_f32_e32 v6, v0
	v_sub_f32_e32 v0, v2, v27
	v_mul_f32_e32 v0, 0x3fb8aa3b, v0
	v_exp_f32_e32 v7, v0
	v_sub_f32_e32 v0, v2, v28
	v_mul_f32_e32 v0, 0x3fb8aa3b, v0
	v_cvt_pk_bf16_f32 v4, v4, v5
	v_pk_mul_f32 v[6:7], v[6:7], v[8:9]
	v_exp_f32_e32 v8, v0
	v_sub_f32_e32 v0, v2, v29
	v_mul_f32_e32 v0, 0x3fb8aa3b, v0
	v_exp_f32_e32 v9, v0
	v_sub_f32_e32 v0, v2, v30
	v_cvt_pk_bf16_f32 v5, v6, v7
	v_lshlrev_b32_e32 v7, 16, v23
	v_lshlrev_b32_e32 v6, 16, v19
	v_mul_f32_e32 v0, 0x3fb8aa3b, v0
	v_pk_mul_f32 v[6:7], v[8:9], v[6:7]
	v_exp_f32_e32 v8, v0
	v_sub_f32_e32 v0, v2, v3
	v_mul_f32_e32 v0, 0x3fb8aa3b, v0
	v_exp_f32_e32 v9, v0
	v_mul_u32_u24_e32 v0, 0x90, v15
	v_lshlrev_b32_e32 v3, 4, v14
	v_cvt_pk_bf16_f32 v6, v6, v7
	v_pk_mul_f32 v[8:9], v[8:9], v[10:11]
	v_add3_u32 v0, 0, v0, v3
	v_cvt_pk_bf16_f32 v7, v8, v9
	ds_write_b128 v0, v[4:7]
	s_and_saveexec_b64 s[14:15], vcc
	s_cbranch_execz .LBB0_677
	v_mul_f32_e32 v0, 0x3fb8aa3b, v2
	s_lshl_b64 s[6:7], s[30:31], 8
	v_readlane_b32 s4, v254, 53
	v_exp_f32_e32 v0, v0
	v_readlane_b32 s5, v254, 54
	s_add_u32 s6, s4, s6
	s_addc_u32 s7, s5, s7
	v_ashrrev_i32_e32 v19, 31, v18
	v_lshl_add_u64 v[2:3], v[18:19], 2, s[6:7]
	global_store_dword v[2:3], v0, off
